# v27 plus 64-byte alignment of the two attention inner-loop heads (code placement)
# speedup vs baseline: 1.0021x; 1.0021x over previous
; template <int DQK, bool ALIBI>
; DI void attn_pass(const u16* __restrict__ Qp, int ldq, const u16* __restrict__ Kp, int ldk, const u16* __restrict__ VTp,
;                   int seq_start, int kt_lo, int kt_hi, int q0, float slope2, f32x16 (&O)[4], float& lsum, char* lds) {
;     ...
;   bf16x8 qf[NKS];
;   const u16* qrow = Qp + (size_t)(seq_start + q0 + w * 32 + r) * ldq;
; #pragma unroll
;   for (int ks = 0; ks < NKS; ++ks) qf[ks] = *(const bf16x8*)(qrow + ks * 16 + h * 8);
; #pragma unroll
;   for (int db = 0; db < 4; ++db)
; #pragma unroll
;     for (int e = 0; e < 16; ++e) O[db][e] = 0.f;
;   f32x2 l2 = {0.f, 0.f};
;   const int qw0 = q0 + w * 32;
;   const float qpos = (float)(qw0 + r - 4 * h);
;   u32x4 rk[KPT], rv[2];
;     ...
;   __syncthreads();
;   ATT_GLOAD(kt_lo);
;   ATT_LSTORE(0);
;   if (kt_lo + 1 < kt_hi) ATT_GLOAD(kt_lo + 1);
;   __syncthreads();
.LBB0_1147:
	v_mov_b32_e32 v143, 0
	s_xor_b64 s[60:61], s[44:45], -1
	v_lshlrev_b32_e32 v153, 3, v72
	s_andn2_b64 vcc, exec, s[56:57]
	v_mov_b32_e32 v142, v143
	v_mov_b32_e32 v65, v143
	v_mov_b32_e32 v64, v143
	v_mov_b32_e32 v63, v143
	v_mov_b32_e32 v62, v143
	v_mov_b32_e32 v61, v143
	v_mov_b32_e32 v60, v143
	v_mov_b32_e32 v59, v143
	v_mov_b32_e32 v58, v143
	v_mov_b32_e32 v57, v143
	v_mov_b32_e32 v56, v143
	v_mov_b32_e32 v55, v143
	v_mov_b32_e32 v54, v143
	v_mov_b32_e32 v53, v143
	v_mov_b32_e32 v52, v143
	v_mov_b32_e32 v51, v143
	v_mov_b32_e32 v50, v143
	v_mov_b32_e32 v49, v143
	v_mov_b32_e32 v48, v143
	v_mov_b32_e32 v47, v143
	v_mov_b32_e32 v46, v143
	v_mov_b32_e32 v45, v143
	v_mov_b32_e32 v44, v143
	v_mov_b32_e32 v43, v143
	v_mov_b32_e32 v42, v143
	v_mov_b32_e32 v41, v143
	v_mov_b32_e32 v40, v143
	v_mov_b32_e32 v39, v143
	v_mov_b32_e32 v38, v143
	v_mov_b32_e32 v37, v143
	v_mov_b32_e32 v36, v143
	v_mov_b32_e32 v35, v143
	v_mov_b32_e32 v34, v143
	v_mov_b32_e32 v33, v143
	v_mov_b32_e32 v32, v143
	v_mov_b32_e32 v31, v143
	v_mov_b32_e32 v30, v143
	v_mov_b32_e32 v29, v143
	v_mov_b32_e32 v28, v143
	v_mov_b32_e32 v27, v143
	v_mov_b32_e32 v26, v143
	v_mov_b32_e32 v25, v143
	v_mov_b32_e32 v24, v143
	v_mov_b32_e32 v23, v143
	v_mov_b32_e32 v22, v143
	v_mov_b32_e32 v21, v143
	v_mov_b32_e32 v20, v143
	v_mov_b32_e32 v19, v143
	v_mov_b32_e32 v18, v143
	v_mov_b32_e32 v17, v143
	v_mov_b32_e32 v16, v143
	v_mov_b32_e32 v15, v143
	v_mov_b32_e32 v14, v143
	v_mov_b32_e32 v13, v143
	v_mov_b32_e32 v12, v143
	v_mov_b32_e32 v11, v143
	v_mov_b32_e32 v10, v143
	v_mov_b32_e32 v9, v143
	v_mov_b32_e32 v8, v143
	v_mov_b32_e32 v7, v143
	v_mov_b32_e32 v6, v143
	v_mov_b32_e32 v5, v143
	v_mov_b32_e32 v4, v143
	v_mov_b32_e32 v3, v143
	v_mov_b32_e32 v2, v143
	s_waitcnt lgkmcnt(0)
	s_barrier
	s_cbranch_vccnz .LBB0_1163
	v_or_b32_e32 v2, v129, v71
	v_lshlrev_b32_e32 v3, 2, v72
	v_sub_u32_e32 v2, v2, v3
	v_cvt_f32_i32_e32 v154, v2
	v_add_u32_e32 v2, v70, v73
	v_ashrrev_i32_e32 v4, 3, v2
	v_and_b32_e32 v2, -8, v2
	v_sub_u32_e32 v2, v70, v2
	v_lshlrev_b32_e32 v158, 4, v2
	v_lshlrev_b32_e32 v2, 3, v2
	v_ashrrev_i32_e32 v3, 31, v2
	v_lshl_add_u64 v[136:137], v[2:3], 1, s[6:7]
	v_and_b32_e32 v2, 7, v70
	v_lshlrev_b32_e32 v2, 4, v2
	v_mov_b32_e32 v3, v1
	v_mul_lo_u32 v157, v4, s16
	v_add_u32_e32 v159, s86, v4
	v_lshl_add_u64 v[4:5], v[68:69], 0, v[2:3]
	v_lshl_add_u64 v[2:3], v[66:67], 0, v[2:3]
	v_lshl_add_u64 v[140:141], s[58:59], 0, v[2:3]
	v_mov_b32_e32 v2, 0
	v_or_b32_e32 v155, 31, v129
	v_mul_u32_u24_e32 v156, 0x90, v71
	v_lshl_add_u64 v[138:139], s[58:59], 0, v[4:5]
	s_mov_b32 s87, 0
	s_mov_b32 s89, s83
	v_mov_b32_e32 v3, v2
	v_mov_b32_e32 v4, v2
	v_mov_b32_e32 v5, v2
	v_mov_b32_e32 v6, v2
	v_mov_b32_e32 v7, v2
	v_mov_b32_e32 v8, v2
	v_mov_b32_e32 v9, v2
	v_mov_b32_e32 v10, v2
	v_mov_b32_e32 v11, v2
	v_mov_b32_e32 v12, v2
	v_mov_b32_e32 v13, v2
	v_mov_b32_e32 v14, v2
	v_mov_b32_e32 v15, v2
	v_mov_b32_e32 v16, v2
	v_mov_b32_e32 v17, v2
	v_mov_b32_e32 v18, v2
	v_mov_b32_e32 v19, v2
	v_mov_b32_e32 v20, v2
	v_mov_b32_e32 v21, v2
	v_mov_b32_e32 v22, v2
	v_mov_b32_e32 v23, v2
	v_mov_b32_e32 v24, v2
	v_mov_b32_e32 v25, v2
	v_mov_b32_e32 v26, v2
	v_mov_b32_e32 v27, v2
	v_mov_b32_e32 v28, v2
	v_mov_b32_e32 v29, v2
	v_mov_b32_e32 v30, v2
	v_mov_b32_e32 v31, v2
	v_mov_b32_e32 v32, v2
	v_mov_b32_e32 v33, v2
	v_mov_b32_e32 v34, v2
	v_mov_b32_e32 v35, v2
	v_mov_b32_e32 v36, v2
	v_mov_b32_e32 v37, v2
	v_mov_b32_e32 v38, v2
	v_mov_b32_e32 v39, v2
	v_mov_b32_e32 v40, v2
	v_mov_b32_e32 v41, v2
	v_mov_b32_e32 v42, v2
	v_mov_b32_e32 v43, v2
	v_mov_b32_e32 v44, v2
	v_mov_b32_e32 v45, v2
	v_mov_b32_e32 v46, v2
	v_mov_b32_e32 v47, v2
	v_mov_b32_e32 v48, v2
	v_mov_b32_e32 v49, v2
	v_mov_b32_e32 v50, v2
	v_mov_b32_e32 v51, v2
	v_mov_b32_e32 v52, v2
	v_mov_b32_e32 v53, v2
	v_mov_b32_e32 v54, v2
	v_mov_b32_e32 v55, v2
	v_mov_b32_e32 v56, v2
	v_mov_b32_e32 v57, v2
	v_mov_b32_e32 v58, v2
	v_mov_b32_e32 v59, v2
	v_mov_b32_e32 v60, v2
	v_mov_b32_e32 v61, v2
	v_mov_b32_e32 v62, v2
	v_mov_b32_e32 v63, v2
	v_mov_b32_e32 v64, v2
	v_mov_b32_e32 v65, v2
	v_mov_b32_e32 v142, v2
	v_mov_b32_e32 v143, v2
	.p2align 6

; template <int DQK, bool ALIBI>
; DI void attn_pass(const u16* __restrict__ Qp, int ldq, const u16* __restrict__ Kp, int ldk, const u16* __restrict__ VTp,
;                   int seq_start, int kt_lo, int kt_hi, int q0, float slope2, f32x16 (&O)[4], float& lsum, char* lds) {
;     ...
;   bf16x8 qf[NKS];
;   const u16* qrow = Qp + (size_t)(seq_start + q0 + w * 32 + r) * ldq;
; #pragma unroll
;   for (int ks = 0; ks < NKS; ++ks) qf[ks] = *(const bf16x8*)(qrow + ks * 16 + h * 8);
; #pragma unroll
;   for (int db = 0; db < 4; ++db)
; #pragma unroll
;     for (int e = 0; e < 16; ++e) O[db][e] = 0.f;
;   f32x2 l2 = {0.f, 0.f};
;   const int qw0 = q0 + w * 32;
;   const float qpos = (float)(qw0 + r - 4 * h);
;   u32x4 rk[KPT], rv[2];
;     ...
;   __syncthreads();
;   ATT_GLOAD(kt_lo);
;   ATT_LSTORE(0);
;   if (kt_lo + 1 < kt_hi) ATT_GLOAD(kt_lo + 1);
;   __syncthreads();
.LBB0_1190:
	s_or_b64 exec, exec, s[44:45]
	s_lshl_b64 s[44:45], s[52:53], 14
	s_add_u32 s44, s71, s44
	s_addc_u32 s45, s72, s45
	v_mov_b32_e32 v15, v1
	v_lshl_add_u64 v[6:7], s[44:45], 0, v[14:15]
	v_lshl_add_u64 v[6:7], v[6:7], 0, s[80:81]
	v_lshl_add_u64 v[8:9], v[6:7], 0, v[10:11]
	v_lshl_add_u64 v[6:7], v[6:7], 0, v[12:13]
	global_load_dwordx4 v[130:133], v[8:9], off
	global_load_dwordx4 v[134:137], v[6:7], off
	v_add_u32_e32 v8, v24, v23
	v_mul_lo_u32 v6, v8, 12
	v_sub_u32_e32 v6, v20, v6
	v_lshlrev_b32_e32 v156, 4, v6
	v_lshlrev_b32_e32 v6, 3, v6
	v_ashrrev_i32_e32 v7, 31, v6
	v_lshl_add_u64 v[140:141], v[6:7], 1, s[48:49]
	v_lshl_add_u64 v[142:143], v[2:3], 1, s[48:49]
	s_sub_i32 s48, 1, s66
	s_add_u32 s44, s70, s50
	v_mul_lo_u32 v157, v4, s85
	v_add_u32_e32 v160, 0x80, v4
	s_addc_u32 s45, s69, s51
	v_and_b32_e32 v4, 7, v20
	v_lshlrev_b32_e32 v158, 4, v5
	v_lshl_add_u64 v[2:3], s[44:45], 0, v[12:13]
	v_lshlrev_b32_e32 v4, 4, v4
	v_mov_b32_e32 v5, v1
	v_lshl_add_u64 v[2:3], v[2:3], 0, v[4:5]
	v_lshl_add_u64 v[144:145], s[46:47], 0, v[2:3]
	v_lshl_add_u64 v[2:3], s[44:45], 0, v[10:11]
	v_lshl_add_u64 v[2:3], v[2:3], 0, v[4:5]
	v_lshlrev_b32_e32 v16, 3, v22
	v_lshl_add_u64 v[146:147], s[46:47], 0, v[2:3]
	v_mov_b32_e32 v2, 0
	v_mul_u32_u24_e32 v154, 0xd0, v21
	v_mul_lo_u32 v155, v8, s85
	v_mul_u32_u24_e32 v151, 0x90, v21
	v_add_u32_e32 v159, 0x80, v8
	s_mov_b32 s49, 2
	v_lshlrev_b32_e32 v161, 1, v16
	v_mov_b32_e32 v3, v2
	v_mov_b32_e32 v4, v2
	v_mov_b32_e32 v5, v2
	v_mov_b32_e32 v6, v2
	v_mov_b32_e32 v7, v2
	v_mov_b32_e32 v8, v2
	v_mov_b32_e32 v9, v2
	v_mov_b32_e32 v10, v2
	v_mov_b32_e32 v11, v2
	v_mov_b32_e32 v12, v2
	v_mov_b32_e32 v13, v2
	v_mov_b32_e32 v14, v2
	v_mov_b32_e32 v15, v2
	v_mov_b32_e32 v16, v2
	v_mov_b32_e32 v17, v2
	v_mov_b32_e32 v18, v2
	v_mov_b32_e32 v19, v2
	v_mov_b32_e32 v20, v2
	v_mov_b32_e32 v21, v2
	v_mov_b32_e32 v22, v2
	v_mov_b32_e32 v23, v2
	v_mov_b32_e32 v24, v2
	v_mov_b32_e32 v25, v2
	v_mov_b32_e32 v26, v2
	v_mov_b32_e32 v27, v2
	v_mov_b32_e32 v28, v2
	v_mov_b32_e32 v29, v2
	v_mov_b32_e32 v30, v2
	v_mov_b32_e32 v31, v2
	v_mov_b32_e32 v32, v2
	v_mov_b32_e32 v33, v2
	v_mov_b32_e32 v34, v2
	v_mov_b32_e32 v35, v2
	v_mov_b32_e32 v36, v2
	v_mov_b32_e32 v37, v2
	v_mov_b32_e32 v38, v2
	v_mov_b32_e32 v39, v2
	v_mov_b32_e32 v40, v2
	v_mov_b32_e32 v41, v2
	v_mov_b32_e32 v42, v2
	v_mov_b32_e32 v43, v2
	v_mov_b32_e32 v44, v2
	v_mov_b32_e32 v45, v2
	v_mov_b32_e32 v46, v2
	v_mov_b32_e32 v47, v2
	v_mov_b32_e32 v48, v2
	v_mov_b32_e32 v49, v2
	v_mov_b32_e32 v50, v2
	v_mov_b32_e32 v51, v2
	v_mov_b32_e32 v52, v2
	v_mov_b32_e32 v53, v2
	v_mov_b32_e32 v54, v2
	v_mov_b32_e32 v55, v2
	v_mov_b32_e32 v56, v2
	v_mov_b32_e32 v57, v2
	v_mov_b32_e32 v58, v2
	v_mov_b32_e32 v59, v2
	v_mov_b32_e32 v60, v2
	v_mov_b32_e32 v61, v2
	v_mov_b32_e32 v62, v2
	v_mov_b32_e32 v63, v2
	v_mov_b32_e32 v64, v2
	v_mov_b32_e32 v65, v2
	v_mov_b32_e32 v148, v2
	v_mov_b32_e32 v149, v2
	s_waitcnt lgkmcnt(0)
	s_barrier
	s_branch .LBB0_1193
	.p2align 6
